# v16: v15 plus a one-off half-K-tile stagger (s_sleep 16) for workgroups >= 256 at the start of the FFN-up and FFN-down GEMM phases
# baseline (speedup 1.0000x reference)
; #define LDSP(T, p) ((__attribute__((address_space(3))) T*)(p))
; DI int tidx() { int t = threadIdx.x; asm volatile("" : "+v"(t)); return t; }
; DI void gemm_issue_first(const bf16_t* __restrict__ A, int lda, const bf16_t* __restrict__ Bt, int ldb, int m0, int n0, char* smem) {
;   const int tid = tidx(), wave = tid >> 6, lane = tid & 63;
; #pragma unroll
;   for (int i = 0; i < 4; ++i) {
;     const int row = (i * 4 + wave) * 8 + (lane >> 3), chunk = (lane & 7) ^ ((row >> 1) & 7);
;     __builtin_amdgcn_global_load_lds((const unsigned*)(A + (size_t)(m0 + row) * lda + chunk * 8), LDSP(unsigned, smem + (i * 4 + wave) * 1024), 16, 0, 0);
;     __builtin_amdgcn_global_load_lds((const unsigned*)(Bt + (size_t)(n0 + row) * ldb + chunk * 8), LDSP(unsigned, smem + 16384 + (i * 4 + wave) * 1024), 16, 0, 0);
;   }
; }
; template <int EPI>
; DI void gemm_phase(const GArgs& g, char* smem) {
;   const int ntm = g.M / 128, ntn = g.Npad / 128;
;   const int tid = tidx(), lane = tid & 63, wave = tid >> 6;
;   if ((int)blockIdx.x < ntm * ntn) gemm_issue_first(g.A, g.lda, g.Bt, g.K, (blockIdx.x % ntm) * 128, (blockIdx.x / ntm) * 128, smem);
;   for (int tile = blockIdx.x; tile < ntm * ntn; tile += gridDim.x) {
;     const int m0 = (tile % ntm) * 128, n0 = (tile / ntm) * 128;
.LBB0_1157:
	s_or_b64 exec, exec, s[0:1]
	v_readlane_b32 s6, v254, 46
	v_readlane_b32 s0, v253, 24
	v_readlane_b32 s7, v254, 47
	v_readlane_b32 s1, v253, 25
	s_mov_b32 s7, s97
	s_waitcnt lgkmcnt(0)
	v_mov_b32_e32 v2, v190
	s_andn2_b64 vcc, exec, s[0:1]
	s_barrier
	s_cmpk_lt_u32 s82, 0x100
	s_cbranch_scc1 .Lstag_skip0
	s_sleep 16
.Lstag_skip0:
	s_cbranch_vccnz .LBB0_1168
	v_mov_b32_e32 v3, v190
	v_readlane_b32 s3, v251, 40
	v_ashrrev_i32_e32 v6, 6, v3
	v_bfe_u32 v7, v3, 3, 3
	v_lshl_or_b32 v8, v6, 3, v7
	v_lshrrev_b32_e32 v0, 1, v8
	v_add_u32_e32 v4, s3, v8
	s_mul_i32 s0, s6, 0x2c00000
	v_readlane_b32 s2, v251, 3
	v_xor_b32_e32 v0, v0, v3
	v_ashrrev_i32_e32 v5, 31, v4
	v_readlane_b32 s4, v251, 18
	s_mul_hi_u32 s1, s6, 0x2c00000
	s_add_u32 s0, s2, s0
	v_readlane_b32 s2, v251, 4
	v_lshlrev_b64 v[4:5], 12, v[4:5]
	v_readlane_b32 s5, v251, 19
	v_lshlrev_b32_e32 v0, 4, v0
	v_lshlrev_b32_e32 v9, 10, v6
	s_addc_u32 s1, s2, s1
	v_lshl_add_u64 v[4:5], s[4:5], 0, v[4:5]
	v_and_b32_e32 v0, 0x70, v0
	v_readfirstlane_b32 s2, v9
	v_lshl_add_u64 v[4:5], v[4:5], 0, v[0:1]
	s_mov_b32 m0, s2
	v_readlane_b32 s8, v251, 41
	global_load_lds_dwordx4 v[4:5], off
	s_nop 0
	v_add_u32_e32 v4, s8, v8
	v_ashrrev_i32_e32 v5, 31, v4
	v_lshlrev_b64 v[4:5], 12, v[4:5]
	v_lshl_add_u64 v[4:5], s[0:1], 0, v[4:5]
	v_lshl_add_u64 v[4:5], v[4:5], 0, v[0:1]
	v_add_u32_e32 v0, 0x4000, v9
	v_add_u32_e32 v8, 4, v6
	v_readfirstlane_b32 s2, v0
	s_mov_b32 m0, s2
	v_lshl_or_b32 v9, v8, 3, v7
	global_load_lds_dwordx4 v[4:5], off
	v_lshrrev_b32_e32 v0, 1, v9
	v_add_u32_e32 v4, s3, v9
	v_xor_b32_e32 v0, v0, v3
	v_ashrrev_i32_e32 v5, 31, v4
	v_lshlrev_b64 v[4:5], 12, v[4:5]
	v_lshlrev_b32_e32 v0, 4, v0
	v_lshlrev_b32_e32 v8, 10, v8
	v_lshl_add_u64 v[4:5], s[4:5], 0, v[4:5]
	v_and_b32_e32 v0, 0x70, v0
	v_readfirstlane_b32 s2, v8
	v_lshl_add_u64 v[4:5], v[4:5], 0, v[0:1]
	s_mov_b32 m0, s2
	s_nop 0
	global_load_lds_dwordx4 v[4:5], off
	v_add_u32_e32 v4, s8, v9
	v_ashrrev_i32_e32 v5, 31, v4
	v_lshlrev_b64 v[4:5], 12, v[4:5]
	v_lshl_add_u64 v[4:5], s[0:1], 0, v[4:5]
	v_lshl_add_u64 v[4:5], v[4:5], 0, v[0:1]
	v_add_u32_e32 v0, 0x4000, v8
	v_add_u32_e32 v8, 8, v6
	v_readfirstlane_b32 s2, v0
	s_mov_b32 m0, s2
	v_lshl_or_b32 v9, v8, 3, v7
	global_load_lds_dwordx4 v[4:5], off
	v_lshrrev_b32_e32 v0, 1, v9
	v_add_u32_e32 v4, s3, v9
	v_xor_b32_e32 v0, v0, v3
	v_ashrrev_i32_e32 v5, 31, v4
	v_lshlrev_b64 v[4:5], 12, v[4:5]
	v_lshlrev_b32_e32 v0, 4, v0
	v_lshlrev_b32_e32 v8, 10, v8
	v_lshl_add_u64 v[4:5], s[4:5], 0, v[4:5]
	v_and_b32_e32 v0, 0x70, v0
	v_readfirstlane_b32 s2, v8
	v_lshl_add_u64 v[4:5], v[4:5], 0, v[0:1]
	s_mov_b32 m0, s2
	v_add_u32_e32 v6, 12, v6
	global_load_lds_dwordx4 v[4:5], off
	v_add_u32_e32 v4, s8, v9
	v_ashrrev_i32_e32 v5, 31, v4
	v_lshlrev_b64 v[4:5], 12, v[4:5]
	v_lshl_add_u64 v[4:5], s[0:1], 0, v[4:5]
	v_lshl_add_u64 v[4:5], v[4:5], 0, v[0:1]
	v_add_u32_e32 v0, 0x4000, v8
	v_lshl_or_b32 v7, v6, 3, v7
	v_readfirstlane_b32 s2, v0
	s_mov_b32 m0, s2
	v_lshrrev_b32_e32 v0, 1, v7
	global_load_lds_dwordx4 v[4:5], off
	v_add_u32_e32 v4, s3, v7
	v_xor_b32_e32 v0, v0, v3
	v_ashrrev_i32_e32 v5, 31, v4
	v_lshlrev_b64 v[4:5], 12, v[4:5]
	v_lshlrev_b32_e32 v0, 4, v0
	v_lshlrev_b32_e32 v3, 10, v6
	v_lshl_add_u64 v[4:5], s[4:5], 0, v[4:5]
	v_and_b32_e32 v0, 0x70, v0
	v_readfirstlane_b32 s2, v3
	v_lshl_add_u64 v[4:5], v[4:5], 0, v[0:1]
	s_mov_b32 m0, s2
	s_mov_b32 s4, s82
	global_load_lds_dwordx4 v[4:5], off
	v_add_u32_e32 v4, s8, v7
	v_ashrrev_i32_e32 v5, 31, v4
	v_lshlrev_b64 v[4:5], 12, v[4:5]
	v_lshl_add_u64 v[4:5], s[0:1], 0, v[4:5]
	v_lshl_add_u64 v[4:5], v[4:5], 0, v[0:1]
	v_add_u32_e32 v0, 0x4000, v3
	v_and_b32_e32 v3, 15, v2
	v_readfirstlane_b32 s2, v0
	s_mov_b32 m0, s2
	v_ashrrev_i32_e32 v0, 1, v2
	global_load_lds_dwordx4 v[4:5], off
	s_movk_i32 s2, 0xffe0
	v_and_or_b32 v166, v0, s2, v3
	v_lshrrev_b32_e32 v0, 2, v2
	v_and_b32_e32 v167, 12, v0
	s_branch .LBB0_1160

; #define LDSP(T, p) ((__attribute__((address_space(3))) T*)(p))
; DI int tidx() { int t = threadIdx.x; asm volatile("" : "+v"(t)); return t; }
; DI void gemm_issue_first(const bf16_t* __restrict__ A, int lda, const bf16_t* __restrict__ Bt, int ldb, int m0, int n0, char* smem) {
;   const int tid = tidx(), wave = tid >> 6, lane = tid & 63;
; #pragma unroll
;   for (int i = 0; i < 4; ++i) {
;     const int row = (i * 4 + wave) * 8 + (lane >> 3), chunk = (lane & 7) ^ ((row >> 1) & 7);
;     __builtin_amdgcn_global_load_lds((const unsigned*)(A + (size_t)(m0 + row) * lda + chunk * 8), LDSP(unsigned, smem + (i * 4 + wave) * 1024), 16, 0, 0);
;     __builtin_amdgcn_global_load_lds((const unsigned*)(Bt + (size_t)(n0 + row) * ldb + chunk * 8), LDSP(unsigned, smem + 16384 + (i * 4 + wave) * 1024), 16, 0, 0);
;   }
; }
; template <int EPI>
; DI void gemm_phase(const GArgs& g, char* smem) {
;   const int ntm = g.M / 128, ntn = g.Npad / 128;
;   const int tid = tidx(), lane = tid & 63, wave = tid >> 6;
;   if ((int)blockIdx.x < ntm * ntn) gemm_issue_first(g.A, g.lda, g.Bt, g.K, (blockIdx.x % ntm) * 128, (blockIdx.x / ntm) * 128, smem);
;   for (int tile = blockIdx.x; tile < ntm * ntn; tile += gridDim.x) {
;     const int m0 = (tile % ntm) * 128, n0 = (tile / ntm) * 128;
.LBB0_1216:
	s_or_b64 exec, exec, s[0:1]
	v_readlane_b32 s0, v251, 14
	v_readlane_b32 s1, v251, 15
	s_waitcnt lgkmcnt(0)
	v_mov_b32_e32 v2, v190
	s_and_b64 vcc, exec, s[0:1]
	s_barrier
	s_cmpk_lt_u32 s82, 0x100
	s_cbranch_scc1 .Lstag_skip1
	s_sleep 16
.Lstag_skip1:
	s_cbranch_vccnz .LBB0_1227
	v_mov_b32_e32 v3, v190
	s_mul_i32 s0, s6, 0x1600000
	v_ashrrev_i32_e32 v10, 6, v3
	v_bfe_u32 v11, v3, 3, 3
	v_lshl_or_b32 v8, v10, 3, v11
	v_readlane_b32 s2, v251, 5
	v_lshrrev_b32_e32 v0, 1, v8
	v_readlane_b32 s4, v251, 40
	s_mul_hi_u32 s1, s6, 0x1600000
	s_add_u32 s0, s2, s0
	v_readlane_b32 s2, v251, 6
	v_xor_b32_e32 v0, v0, v3
	v_add_u32_e32 v6, s4, v8
	v_mov_b64_e32 v[4:5], s[86:87]
	s_movk_i32 s8, 0x2c00
	s_addc_u32 s1, s2, s1
	v_mad_i64_i32 v[6:7], s[2:3], v6, s8, v[4:5]
	v_lshlrev_b32_e32 v0, 4, v0
	v_lshlrev_b32_e32 v12, 10, v10
	v_and_b32_e32 v0, 0x70, v0
	v_readfirstlane_b32 s2, v12
	v_lshl_add_u64 v[6:7], v[6:7], 0, v[0:1]
	s_mov_b32 m0, s2
	v_readlane_b32 s5, v251, 41
	global_load_lds_dwordx4 v[6:7], off
	s_nop 0
	v_add_u32_e32 v8, s5, v8
	v_mov_b64_e32 v[6:7], s[0:1]
	v_mad_i64_i32 v[8:9], s[2:3], v8, s8, v[6:7]
	v_lshl_add_u64 v[8:9], v[8:9], 0, v[0:1]
	v_add_u32_e32 v0, 0x4000, v12
	v_add_u32_e32 v12, 4, v10
	v_readfirstlane_b32 s2, v0
	v_lshl_or_b32 v13, v12, 3, v11
	s_mov_b32 m0, s2
	v_lshrrev_b32_e32 v0, 1, v13
	global_load_lds_dwordx4 v[8:9], off
	v_xor_b32_e32 v0, v0, v3
	v_add_u32_e32 v8, s4, v13
	v_mad_i64_i32 v[8:9], s[2:3], v8, s8, v[4:5]
	v_lshlrev_b32_e32 v0, 4, v0
	v_lshlrev_b32_e32 v12, 10, v12
	v_and_b32_e32 v0, 0x70, v0
	v_readfirstlane_b32 s2, v12
	v_lshl_add_u64 v[8:9], v[8:9], 0, v[0:1]
	s_mov_b32 m0, s2
	s_nop 0
	global_load_lds_dwordx4 v[8:9], off
	v_add_u32_e32 v8, s5, v13
	v_mad_i64_i32 v[8:9], s[2:3], v8, s8, v[6:7]
	v_lshl_add_u64 v[8:9], v[8:9], 0, v[0:1]
	v_add_u32_e32 v0, 0x4000, v12
	v_add_u32_e32 v12, 8, v10
	v_readfirstlane_b32 s2, v0
	v_lshl_or_b32 v13, v12, 3, v11
	s_mov_b32 m0, s2
	v_lshrrev_b32_e32 v0, 1, v13
	global_load_lds_dwordx4 v[8:9], off
	v_xor_b32_e32 v0, v0, v3
	v_add_u32_e32 v8, s4, v13
	v_mad_i64_i32 v[8:9], s[2:3], v8, s8, v[4:5]
	v_lshlrev_b32_e32 v0, 4, v0
	v_lshlrev_b32_e32 v12, 10, v12
	v_and_b32_e32 v0, 0x70, v0
	v_readfirstlane_b32 s2, v12
	v_lshl_add_u64 v[8:9], v[8:9], 0, v[0:1]
	s_mov_b32 m0, s2
	s_nop 0
	global_load_lds_dwordx4 v[8:9], off
	v_add_u32_e32 v8, s5, v13
	v_mad_i64_i32 v[8:9], s[2:3], v8, s8, v[6:7]
	v_lshl_add_u64 v[8:9], v[8:9], 0, v[0:1]
	v_add_u32_e32 v0, 0x4000, v12
	s_nop 0
	v_readfirstlane_b32 s2, v0
	s_mov_b32 m0, s2
	s_nop 0
	global_load_lds_dwordx4 v[8:9], off
	v_add_u32_e32 v8, 12, v10
	v_lshl_or_b32 v9, v8, 3, v11
	v_lshrrev_b32_e32 v0, 1, v9
	v_xor_b32_e32 v0, v0, v3
	v_add_u32_e32 v3, s4, v9
	v_mad_i64_i32 v[4:5], s[2:3], v3, s8, v[4:5]
	v_lshlrev_b32_e32 v0, 4, v0
	v_lshlrev_b32_e32 v3, 10, v8
	v_and_b32_e32 v0, 0x70, v0
	v_readfirstlane_b32 s2, v3
	v_lshl_add_u64 v[4:5], v[4:5], 0, v[0:1]
	s_mov_b32 m0, s2
	s_mov_b32 s4, s82
	global_load_lds_dwordx4 v[4:5], off
	v_add_u32_e32 v4, s5, v9
	v_mad_i64_i32 v[4:5], s[2:3], v4, s8, v[6:7]
	v_lshl_add_u64 v[4:5], v[4:5], 0, v[0:1]
	v_add_u32_e32 v0, 0x4000, v3
	v_and_b32_e32 v3, 15, v2
	v_readfirstlane_b32 s2, v0
	s_mov_b32 m0, s2
	v_ashrrev_i32_e32 v0, 1, v2
	global_load_lds_dwordx4 v[4:5], off
	s_movk_i32 s2, 0xffe0
	v_and_or_b32 v166, v0, s2, v3
	v_lshrrev_b32_e32 v0, 2, v2
	v_and_b32_e32 v167, 12, v0
	s_branch .LBB0_1219
